# nt hints on once-touched streams: x loads in P0 row loop, xb loads and out stores in the final phase; on top of v44
# baseline (speedup 1.0000x reference)
; __device__ __forceinline__ unsigned pk2(float lo, float hi) { f32x2 v = {lo, hi}; bf16x2_t b = __builtin_convertvector(v, bf16x2_t); return __builtin_bit_cast(unsigned, b); }
; __device__ __forceinline__ void p0_phase(const Args& a, LAS unsigned char* lds, int G, int wg, int part, bool split) {
;     ...
;     for (int m = gw; m < MT; m += NGW) {
;         const f32x4* xr = (const f32x4*)(x + (size_t)m * DM) + lane; float s = 0.f;
;         unsigned long long* o8 = (unsigned long long*)(xb + (size_t)m * DM) + lane;
; #pragma unroll
;         for (int j = 0; j < 4; ++j) { const f32x4 v = xr[64 * j]; s += (v.x * v.x + v.y * v.y) + (v.z * v.z + v.w * v.w);
;             o8[64 * j] = (unsigned long long)pk2(v.x, v.y) | ((unsigned long long)pk2(v.z, v.w) << 32); }
;         s = wave_sum(s);
;         if (lane < 16) ssq[(size_t)m * 16 + lane] = (lane == 0) ? s : 0.f;
;     }
.LBB0_126:
	s_waitcnt lgkmcnt(0)
	global_load_dwordx4 v[12:15], v[4:5], off offset:-3072 nt
	global_load_dwordx4 v[16:19], v[4:5], off offset:-2048 nt
	global_load_dwordx4 v[20:23], v[4:5], off offset:-1024 nt
	global_load_dwordx4 v[24:27], v[4:5], off nt
	s_waitcnt vmcnt(3)
	v_cvt_pk_bf16_f32 v28, v12, v13
	v_cvt_pk_bf16_f32 v29, v14, v15
	global_store_dwordx2 v[2:3], v[28:29], off offset:-1024
	v_mul_f32_e32 v13, v13, v13
	v_mul_f32_e32 v15, v15, v15
	v_fmac_f32_e32 v13, v12, v12
	v_fmac_f32_e32 v15, v14, v14
	v_add_f32_e32 v12, v13, v15
	s_waitcnt vmcnt(3)
	v_cvt_pk_bf16_f32 v30, v16, v17
	v_cvt_pk_bf16_f32 v31, v18, v19
	global_store_dwordx2 v[2:3], v[30:31], off offset:-512
	v_mul_f32_e32 v13, v17, v17
	v_mul_f32_e32 v14, v19, v19
	v_fmac_f32_e32 v13, v16, v16
	v_fmac_f32_e32 v14, v18, v18
	v_add_f32_e32 v13, v13, v14
	v_add_f32_e32 v12, v12, v13
	s_waitcnt vmcnt(3)
	v_cvt_pk_bf16_f32 v32, v20, v21
	v_cvt_pk_bf16_f32 v33, v22, v23
	global_store_dwordx2 v[2:3], v[32:33], off
	v_mul_f32_e32 v13, v21, v21
	v_mul_f32_e32 v14, v23, v23
	v_fmac_f32_e32 v13, v20, v20
	v_fmac_f32_e32 v14, v22, v22
	v_add_f32_e32 v13, v13, v14
	v_add_f32_e32 v12, v12, v13
	s_waitcnt vmcnt(3)
	v_mul_f32_e32 v13, v25, v25
	v_mul_f32_e32 v14, v27, v27
	v_fmac_f32_e32 v13, v24, v24
	v_fmac_f32_e32 v14, v26, v26
	v_add_f32_e32 v13, v13, v14
	v_add_f32_e32 v12, v12, v13
	ds_bpermute_b32 v13, v6, v12
	v_cvt_pk_bf16_f32 v14, v24, v25
	v_cvt_pk_bf16_f32 v15, v26, v27
	global_store_dwordx2 v[2:3], v[14:15], off offset:512
	s_waitcnt lgkmcnt(0)
	v_add_f32_e32 v12, v12, v13
	ds_bpermute_b32 v13, v7, v12
	s_waitcnt lgkmcnt(0)
	v_add_f32_e32 v12, v12, v13
	ds_bpermute_b32 v13, v8, v12
	s_waitcnt lgkmcnt(0)
	v_add_f32_e32 v12, v12, v13
	ds_bpermute_b32 v13, v9, v12
	s_waitcnt lgkmcnt(0)
	v_add_f32_e32 v12, v12, v13
	ds_bpermute_b32 v13, v10, v12
	s_waitcnt lgkmcnt(0)
	v_add_f32_e32 v12, v12, v13
	ds_bpermute_b32 v13, v11, v12
	s_and_saveexec_b64 s[6:7], vcc
	s_cbranch_execz .LBB0_125
	s_waitcnt lgkmcnt(0)
	v_add_f32_e32 v12, v12, v13
	v_cndmask_b32_e64 v12, 0, v12, s[4:5]
	global_store_dword v[0:1], v12, off
	s_branch .LBB0_125

; __device__ __forceinline__ void final_phase(const bf16_t* xb, float* out, const float* ssq, const float* gain, int G, int wg) {
;     ...
;     for (int m = gw; m < MT; m += NGW) {
;         const float rs = __builtin_amdgcn_rsqf(pg8::ssq_row(ssq, m) * (1.f / 1024.f) + EPS);
;         const u32x2* xr = (const u32x2*)(xb + (size_t)m * DM) + lane; f32x4* orow = (f32x4*)(out + (size_t)m * DM) + lane;
; #pragma unroll
;         for (int j = 0; j < 4; ++j) { const u32x2 w = xr[64 * j];
;             const f32x4 v = {__builtin_bit_cast(float, w.x << 16), __builtin_bit_cast(float, w.x & 0xffff0000u), __builtin_bit_cast(float, w.y << 16), __builtin_bit_cast(float, w.y & 0xffff0000u)};
;             orow[64 * j] = v * rs * gv[j]; }
;     }
.LBB0_1927:
	global_load_dwordx4 v[24:27], v[16:17], off offset:-32
	global_load_dwordx4 v[28:31], v[16:17], off
	global_load_dwordx4 v[32:35], v[16:17], off offset:-16
	global_load_dwordx4 v[36:39], v[16:17], off offset:16
	global_load_dwordx2 v[40:41], v[20:21], off offset:-1024 nt
	global_load_dwordx2 v[44:45], v[20:21], off offset:-512 nt
	global_load_dwordx2 v[46:47], v[20:21], off nt
	global_load_dwordx2 v[48:49], v[20:21], off offset:512 nt
	v_add_u32_e32 v22, s12, v22
	v_cmp_lt_i32_e32 vcc, s8, v22
	v_lshl_add_u64 v[16:17], v[16:17], 0, s[2:3]
	v_lshl_add_u64 v[20:21], v[20:21], 0, s[6:7]
	s_or_b64 s[10:11], vcc, s[10:11]
	s_waitcnt vmcnt(7)
	v_mov_b32_e32 v42, v24
	s_waitcnt vmcnt(6)
	v_mov_b32_e32 v43, v28
	v_mov_b32_e32 v28, v25
	v_mov_b32_e32 v24, v26
	v_mov_b32_e32 v25, v30
	v_mov_b32_e32 v30, v27
	s_waitcnt vmcnt(5)
	v_mov_b32_e32 v26, v32
	s_waitcnt vmcnt(4)
	v_mov_b32_e32 v27, v36
	v_mov_b32_e32 v36, v33
	v_mov_b32_e32 v32, v34
	v_mov_b32_e32 v33, v38
	v_mov_b32_e32 v38, v35
	v_pk_add_f32 v[28:29], v[42:43], v[28:29]
	v_pk_add_f32 v[24:25], v[24:25], v[30:31]
	v_pk_add_f32 v[26:27], v[26:27], v[36:37]
	v_pk_add_f32 v[30:31], v[32:33], v[38:39]
	v_pk_add_f32 v[24:25], v[28:29], v[24:25]
	v_pk_add_f32 v[26:27], v[26:27], v[30:31]
	s_waitcnt vmcnt(3)
	v_lshlrev_b32_e32 v34, 16, v40
	v_pk_add_f32 v[24:25], v[24:25], v[26:27]
	v_and_b32_e32 v35, 0xffff0000, v40
	v_add_f32_e32 v24, v24, v25
	v_fmamk_f32 v24, v24, 0x3a800000, v23
	v_rsq_f32_e32 v28, v24
	v_lshlrev_b32_e32 v40, 16, v41
	v_and_b32_e32 v41, 0xffff0000, v41
	v_pk_mul_f32 v[24:25], v[28:29], v[34:35] op_sel_hi:[0,1]
	v_pk_mul_f32 v[26:27], v[28:29], v[40:41] op_sel_hi:[0,1]
	v_pk_mul_f32 v[26:27], v[2:3], v[26:27]
	v_pk_mul_f32 v[24:25], v[0:1], v[24:25]
	global_store_dwordx4 v[18:19], v[24:27], off offset:-2048 nt
	s_waitcnt vmcnt(3)
	s_nop 1
	v_lshlrev_b32_e32 v26, 16, v44
	v_and_b32_e32 v27, 0xffff0000, v44
	v_lshlrev_b32_e32 v24, 16, v45
	v_and_b32_e32 v25, 0xffff0000, v45
	v_pk_mul_f32 v[30:31], v[28:29], v[26:27] op_sel_hi:[0,1]
	v_pk_mul_f32 v[24:25], v[28:29], v[24:25] op_sel_hi:[0,1]
	v_pk_mul_f32 v[26:27], v[6:7], v[24:25]
	v_pk_mul_f32 v[24:25], v[4:5], v[30:31]
	global_store_dwordx4 v[18:19], v[24:27], off offset:-1024 nt
	s_waitcnt vmcnt(3)
	s_nop 1
	v_lshlrev_b32_e32 v26, 16, v46
	v_and_b32_e32 v27, 0xffff0000, v46
	v_lshlrev_b32_e32 v24, 16, v47
	v_and_b32_e32 v25, 0xffff0000, v47
	v_pk_mul_f32 v[30:31], v[28:29], v[26:27] op_sel_hi:[0,1]
	v_pk_mul_f32 v[24:25], v[28:29], v[24:25] op_sel_hi:[0,1]
	v_pk_mul_f32 v[26:27], v[10:11], v[24:25]
	v_pk_mul_f32 v[24:25], v[8:9], v[30:31]
	global_store_dwordx4 v[18:19], v[24:27], off nt
	s_waitcnt vmcnt(3)
	s_nop 1
	v_lshlrev_b32_e32 v26, 16, v48
	v_and_b32_e32 v27, 0xffff0000, v48
	v_lshlrev_b32_e32 v24, 16, v49
	v_and_b32_e32 v25, 0xffff0000, v49
	v_pk_mul_f32 v[30:31], v[28:29], v[26:27] op_sel_hi:[0,1]
	v_pk_mul_f32 v[24:25], v[28:29], v[24:25] op_sel_hi:[0,1]
	v_pk_mul_f32 v[26:27], v[14:15], v[24:25]
	v_pk_mul_f32 v[24:25], v[12:13], v[30:31]
	global_store_dwordx4 v[18:19], v[24:27], off offset:1024 nt
	v_lshl_add_u64 v[18:19], v[18:19], 0, s[4:5]
	s_andn2_b64 exec, exec, s[10:11]
	s_cbranch_execnz .LBB0_1927
